# w_in deferral extended to two stages (rest of round-1 tiles + first k-blocks of round-2/3 tiles, then the rest), deferred tiles stored write-through (sc1) so publishing needs no L2 write-back
# speedup vs baseline: 1.0251x; 1.0042x over previous
; #define LAS __attribute__((address_space(3)))
; __device__ __forceinline__ void p0_transpose_item(const float* W, int K, int N, bf16_t* WT, const float* kscale, LAS float* scr, int item, int lane) {
;     const int nblk = N / 32, kb = item / nblk, nb = item % nblk, k0 = 64 * kb, n0 = 32 * nb;
;     const int n4 = (lane & 7) * 4, kr = lane >> 3;
;     f32x4 v[8];
; #pragma unroll
; __global__ void __launch_bounds__(NWAVES * 64, 2) fwd(Args args) {
;     ...
;         for (int it = gw; it < NITEMS; it += NGW) {
;             int r = it;
;             if (r < I_IN) { p0_transpose_item(w_in, DM, DIN, WinT, nullptr, scr, r, lane); continue; } r -= I_IN;
;             p0_transpose_item(w_proj, PLE, DM, WpT, nullptr, scr, r, lane);
;         }
.LBB0_8:
	s_add_u32 s26, s80, 0x100000
	s_addc_u32 s27, s81, 0
	s_add_u32 s28, s80, 0x200000
	s_addc_u32 s29, s81, 0
	s_add_u32 s24, s80, 0x2e00000
	s_addc_u32 s25, s81, 0
	s_lshr_b32 s60, s92, 6
	s_load_dwordx8 s[8:15], s[0:1], 0x60
	s_cmp_lt_i32 s82, 1
	s_cselect_b64 s[2:3], -1, 0
	s_cmp_gt_i32 s83, 0
	s_cselect_b64 s[4:5], -1, 0
	s_lshl_b32 s6, s60, 14
	s_and_b64 s[4:5], s[2:3], s[4:5]
	s_add_i32 s61, s6, 0
	s_andn2_b64 vcc, exec, s[4:5]
	s_cbranch_vccnz .LBB0_40
	s_load_dwordx8 s[16:23], s[0:1], 0x0
	s_lshl_b32 s4, s95, 3
	v_mbcnt_lo_u32_b32 v0, -1, 0
	s_add_i32 s4, s4, s60
	s_lshl_b32 s6, s78, 3
	v_mbcnt_hi_u32_b32 v8, -1, v0
	s_cmpk_gt_i32 s4, 0x95f
	s_mov_b32 s31, 0
	v_mov_b32_e32 v16, v8
	s_cbranch_scc1 .LBB0_16
	v_and_b32_e32 v2, 7, v16
	v_ashrrev_i32_e32 v9, 3, v16
	v_lshlrev_b32_e32 v6, 4, v2
	s_movk_i32 s5, 0x84
	v_add_u32_e32 v14, s61, v6
	v_mul_lo_u32 v15, v9, s5
	v_mov_b32_e32 v7, 0
	v_mul_u32_u24_e32 v4, 0x420, v2
	v_lshlrev_b32_e32 v5, 2, v9
	v_add_u32_e32 v14, v14, v15
	s_waitcnt lgkmcnt(0)
	v_lshl_add_u64 v[0:1], s[14:15], 0, v[6:7]
	v_add_u32_e32 v10, 8, v9
	v_add_u32_e32 v11, 16, v9
	v_add_u32_e32 v12, 24, v9
	v_lshl_add_u64 v[2:3], s[24:25], 0, v[6:7]
	v_add3_u32 v13, s61, v4, v5
	v_lshl_add_u64 v[4:5], s[22:23], 0, v[6:7]
	v_lshl_add_u64 v[6:7], s[28:29], 0, v[6:7]
	s_lshl_b32 s5, s4, 5
	s_lshl_b32 s7, s6, 5
	v_add_u32_e32 v15, 0x420, v14
	v_add_u32_e32 v17, 0x428, v14
	v_add_u32_e32 v18, 0x840, v14
	v_add_u32_e32 v19, 0x848, v14
	v_add_u32_e32 v20, 0xc60, v14
	v_add_u32_e32 v21, 0xc68, v14
	v_add_u32_e32 v22, 0x1080, v14
	v_add_u32_e32 v23, 0x1088, v14
	v_add_u32_e32 v24, 0x14a0, v14
	v_add_u32_e32 v25, 0x14a8, v14
	v_add_u32_e32 v26, 0x18c0, v14
	v_add_u32_e32 v27, 0x18c8, v14
	v_add_u32_e32 v28, 0x1ce0, v14
	v_add_u32_e32 v29, 0x1ce8, v14
	s_movk_i32 s22, 0x7000
	s_mov_b32 s23, s4
	s_branch .LBB0_12
.LBB0_11:
	s_add_i32 s23, s23, s6
	s_add_i32 s5, s5, s7
	s_cmpk_gt_i32 s23, 0x95f
	s_cbranch_scc1 .LBB0_16
.LBB0_12:
	s_cmpk_lt_i32 s23, 0x100
	s_mov_b64 s[14:15], -1
	s_cbranch_scc1 .LBB0_14
	s_andn2_b64 vcc, exec, s[14:15]
	s_cbranch_vccnz .LBB0_11
	s_branch .LBB0_15

; #define LAS __attribute__((address_space(3)))
; __device__ __forceinline__ unsigned cvtpk(float lo, float hi) { f32x2 v = {lo, hi}; bf16x2_t b = __builtin_convertvector(v, bf16x2_t); return __builtin_bit_cast(unsigned, b); }
; __device__ __forceinline__ void p0_transpose_item(const float* W, int K, int N, bf16_t* WT, const float* kscale, LAS float* scr, int item, int lane) {
;     const int nblk = N / 32, kb = item / nblk, nb = item % nblk, k0 = 64 * kb, n0 = 32 * nb;
;     const int n4 = (lane & 7) * 4, kr = lane >> 3;
;     f32x4 v[8];
; #pragma unroll
;     for (int i = 0; i < 8; ++i) v[i] = __builtin_nontemporal_load((const f32x4*)(W + (size_t)(k0 + kr + 8 * i) * N + n0 + n4));
; #pragma unroll
;     for (int i = 0; i < 8; ++i) { const int kk = kr + 8 * i; const float sc = kscale ? kscale[k0 + kk] : 1.0f; LAS float* d = scr + kk * 33 + n4;
;         d[0] = v[i].x * sc; d[1] = v[i].y * sc; d[2] = v[i].z * sc; d[3] = v[i].w * sc; }
;     asm volatile("s_waitcnt lgkmcnt(0)" ::: "memory");
;     const int c = lane & 7;
; #pragma unroll
;     for (int j = 0; j < 4; ++j) { const int n = (lane >> 3) + 8 * j; const LAS float* sp = scr + (8 * c) * 33 + n;
;         u32x4 o; o.x = cvtpk(sp[0 * 33], sp[1 * 33]); o.y = cvtpk(sp[2 * 33], sp[3 * 33]); o.z = cvtpk(sp[4 * 33], sp[5 * 33]); o.w = cvtpk(sp[6 * 33], sp[7 * 33]);
;         *(u32x4*)(WT + (size_t)(n0 + n) * K + k0 + 8 * c) = o; }
;     asm volatile("s_waitcnt lgkmcnt(0)" ::: "memory");
; }
.LBB0_15:
	s_sub_i32 s34, s23, 0x100
	s_cmpk_lt_u32 s34, 0x800
	s_cbranch_scc0 .Lp0_r1
	s_lshr_b32 s15, s34, 6
	s_and_b32 s34, s34, 63
	s_cmp_ge_u32 s34, 32
	s_cselect_b32 s14, 80, 0
	s_add_i32 s34, s34, s14
	s_branch .Lp0_dec
.Lp0_r1:
	s_sub_i32 s34, s34, 0x800
	s_cmp_ge_u32 s34, 48
	s_cselect_b32 s15, 1, 0
	s_cselect_b32 s14, 48, 0
	s_sub_i32 s34, s34, s14
	s_cmp_ge_u32 s34, 24
	s_cselect_b32 s14, 0x78, 32
	s_add_i32 s34, s34, s14
.Lp0_dec:
	s_lshl_b32 s34, s34, 5
	s_lshl_b32 s14, s15, 6
	s_ashr_i32 s35, s34, 31
	v_add_u32_e32 v60, s14, v9
	v_lshl_add_u64 v[58:59], s[34:35], 2, v[4:5]
	v_mad_i64_i32 v[38:39], s[36:37], v60, s22, v[58:59]
	v_add_u32_e32 v30, 8, v60
	v_mad_i64_i32 v[40:41], s[36:37], v30, s22, v[58:59]
	global_load_dwordx4 v[30:33], v[38:39], off nt
	global_load_dwordx4 v[34:37], v[40:41], off nt
	v_add_u32_e32 v38, 16, v60
	v_mad_i64_i32 v[46:47], s[36:37], v38, s22, v[58:59]
	v_add_u32_e32 v38, 24, v60
	v_mad_i64_i32 v[48:49], s[36:37], v38, s22, v[58:59]
	global_load_dwordx4 v[38:41], v[46:47], off nt
	global_load_dwordx4 v[42:45], v[48:49], off nt
	v_add_u32_e32 v46, 32, v60
	v_mad_i64_i32 v[54:55], s[36:37], v46, s22, v[58:59]
	v_add_u32_e32 v46, 40, v60
	v_mad_i64_i32 v[56:57], s[36:37], v46, s22, v[58:59]
	global_load_dwordx4 v[46:49], v[54:55], off nt
	global_load_dwordx4 v[50:53], v[56:57], off nt
	v_add_u32_e32 v54, 48, v60
	v_mad_i64_i32 v[54:55], s[36:37], v54, s22, v[58:59]
	global_load_dwordx4 v[54:57], v[54:55], off nt
	v_add_u32_e32 v60, 56, v60
	v_mad_i64_i32 v[58:59], s[36:37], v60, s22, v[58:59]
	global_load_dwordx4 v[58:61], v[58:59], off nt
	v_add_u32_e32 v64, s34, v9
	s_ashr_i32 s15, s14, 31
	v_ashrrev_i32_e32 v65, 31, v64
	v_add_u32_e32 v66, 8, v64
	v_lshl_add_u64 v[62:63], s[14:15], 1, v[6:7]
	v_lshlrev_b64 v[68:69], 12, v[64:65]
	v_ashrrev_i32_e32 v67, 31, v66
	v_lshl_add_u64 v[68:69], v[62:63], 0, v[68:69]
	v_lshlrev_b64 v[66:67], 12, v[66:67]
	v_lshl_add_u64 v[66:67], v[62:63], 0, v[66:67]
	s_waitcnt vmcnt(7)
	ds_write2_b32 v14, v30, v31 offset1:1
	ds_write2_b32 v14, v32, v33 offset0:2 offset1:3
	s_waitcnt vmcnt(6)
	ds_write2_b32 v15, v34, v35 offset1:1
	ds_write2_b32 v17, v36, v37 offset1:1
	s_waitcnt vmcnt(5)
	ds_write2_b32 v18, v38, v39 offset1:1
	ds_write2_b32 v19, v40, v41 offset1:1
	s_waitcnt vmcnt(4)
	ds_write2_b32 v20, v42, v43 offset1:1
	ds_write2_b32 v21, v44, v45 offset1:1
	s_waitcnt vmcnt(3)
	ds_write2_b32 v22, v46, v47 offset1:1
	ds_write2_b32 v23, v48, v49 offset1:1
	s_waitcnt vmcnt(2)
	ds_write2_b32 v24, v50, v51 offset1:1
	ds_write2_b32 v25, v52, v53 offset1:1
	s_waitcnt vmcnt(1)
	ds_write2_b32 v26, v54, v55 offset1:1
	ds_write2_b32 v27, v56, v57 offset1:1
	s_waitcnt vmcnt(0)
	ds_write2_b32 v28, v58, v59 offset1:1
	ds_write2_b32 v29, v60, v61 offset1:1
	s_waitcnt lgkmcnt(0)
	ds_read2_b32 v[32:33], v13 offset0:33 offset1:41
	ds_read2_b32 v[34:35], v13 offset1:8
	ds_read2_b32 v[36:37], v13 offset0:66 offset1:74
	ds_read2_b32 v[38:39], v13 offset0:99 offset1:107
	ds_read2_b32 v[40:41], v13 offset0:132 offset1:140
	ds_read2_b32 v[42:43], v13 offset0:165 offset1:173
	ds_read2_b32 v[44:45], v13 offset0:198 offset1:206
	ds_read2_b32 v[46:47], v13 offset0:231 offset1:239
	ds_read2_b32 v[48:49], v13 offset0:49 offset1:57
	ds_read2_b32 v[50:51], v13 offset0:16 offset1:24
	ds_read2_b32 v[52:53], v13 offset0:82 offset1:90
	ds_read2_b32 v[54:55], v13 offset0:115 offset1:123
	ds_read2_b32 v[56:57], v13 offset0:148 offset1:156
	ds_read2_b32 v[58:59], v13 offset0:181 offset1:189
	ds_read2_b32 v[60:61], v13 offset0:214 offset1:222
	ds_read2_b32 v[70:71], v13 offset0:247 offset1:255
	s_waitcnt lgkmcnt(14)
	v_cvt_pk_bf16_f32 v30, v34, v32
	s_waitcnt lgkmcnt(12)
	v_cvt_pk_bf16_f32 v31, v36, v38
	v_cvt_pk_bf16_f32 v34, v35, v33
	s_waitcnt lgkmcnt(10)
	v_cvt_pk_bf16_f32 v32, v40, v42
	s_waitcnt lgkmcnt(8)
	v_cvt_pk_bf16_f32 v33, v44, v46
	v_cvt_pk_bf16_f32 v35, v37, v39
	v_cvt_pk_bf16_f32 v36, v41, v43
	v_cvt_pk_bf16_f32 v37, v45, v47
	global_store_dwordx4 v[68:69], v[30:33], off
	global_store_dwordx4 v[66:67], v[34:37], off
	s_waitcnt lgkmcnt(6)
	v_cvt_pk_bf16_f32 v38, v50, v48
	v_add_u32_e32 v30, 16, v64
	v_ashrrev_i32_e32 v31, 31, v30
	v_add_u32_e32 v34, 24, v64
	v_lshlrev_b64 v[30:31], 12, v[30:31]
	v_ashrrev_i32_e32 v35, 31, v34
	s_waitcnt lgkmcnt(4)
	v_cvt_pk_bf16_f32 v39, v52, v54
	s_waitcnt lgkmcnt(2)
	v_cvt_pk_bf16_f32 v40, v56, v58
	s_waitcnt lgkmcnt(0)
	v_cvt_pk_bf16_f32 v41, v60, v70
	v_lshl_add_u64 v[30:31], v[62:63], 0, v[30:31]
	v_lshlrev_b64 v[34:35], 12, v[34:35]
	global_store_dwordx4 v[30:31], v[38:41], off
	v_cvt_pk_bf16_f32 v30, v51, v49
	v_cvt_pk_bf16_f32 v31, v53, v55
	v_cvt_pk_bf16_f32 v32, v57, v59
	v_cvt_pk_bf16_f32 v33, v61, v71
	v_lshl_add_u64 v[34:35], v[62:63], 0, v[34:35]
	global_store_dwordx4 v[34:35], v[30:33], off
	s_waitcnt lgkmcnt(0)
	s_branch .LBB0_11

; template <class Epi, bool ALIGN_EPI>
; __device__ __forceinline__ void gemm_phase(LAS unsigned char* lds, const Gemm g, const StaticOrder& S, const Epi& E, const int wid) {
;     ...
;         const bool has_next = S.next(ui + 1, nxt);
;         const char* nA = has_next ? (const char*)g.A + (size_t)nxt.pm * tstep : cA; const char* nB = has_next ? (const char*)g.Bt + (size_t)nxt.pn * tstep : cB;
.LBB0_102:
	s_add_i32 s59, s59, 1
	s_cmp_lt_u32 s59, 2
	s_cbranch_scc1 .Ldw_ok
	s_cmp_gt_u32 s59, 3
	s_cbranch_scc1 .Ldw_ok
	s_sub_i32 s5, s59, 1
	s_lshl_b32 s5, s5, 5
.Ldw_poll:
	v_mov_b32_e32 v252, 0
	global_load_dword v252, v252, s[88:89] offset:256 sc1
	s_waitcnt vmcnt(0)
	v_readfirstlane_b32 s4, v252
	s_cmp_ge_u32 s4, s5
	s_cbranch_scc1 .Ldw_ok
	s_sleep 2
	s_branch .Ldw_poll

; #define LAS __attribute__((address_space(3)))
; __device__ __forceinline__ unsigned cvtpk(float lo, float hi) { f32x2 v = {lo, hi}; bf16x2_t b = __builtin_convertvector(v, bf16x2_t); return __builtin_bit_cast(unsigned, b); }
; __device__ __forceinline__ void p0_transpose_item(const float* W, int K, int N, bf16_t* WT, const float* kscale, LAS float* scr, int item, int lane) {
;     const int nblk = N / 32, kb = item / nblk, nb = item % nblk, k0 = 64 * kb, n0 = 32 * nb;
;     const int n4 = (lane & 7) * 4, kr = lane >> 3;
;     f32x4 v[8];
; #pragma unroll
;     for (int i = 0; i < 8; ++i) v[i] = __builtin_nontemporal_load((const f32x4*)(W + (size_t)(k0 + kr + 8 * i) * N + n0 + n4));
; #pragma unroll
;     for (int i = 0; i < 8; ++i) { const int kk = kr + 8 * i; const float sc = kscale ? kscale[k0 + kk] : 1.0f; LAS float* d = scr + kk * 33 + n4;
;         d[0] = v[i].x * sc; d[1] = v[i].y * sc; d[2] = v[i].z * sc; d[3] = v[i].w * sc; }
;     asm volatile("s_waitcnt lgkmcnt(0)" ::: "memory");
;     const int c = lane & 7;
; #pragma unroll
;     for (int j = 0; j < 4; ++j) { const int n = (lane >> 3) + 8 * j; const LAS float* sp = scr + (8 * c) * 33 + n;
;         u32x4 o; o.x = cvtpk(sp[0 * 33], sp[1 * 33]); o.y = cvtpk(sp[2 * 33], sp[3 * 33]); o.z = cvtpk(sp[4 * 33], sp[5 * 33]); o.w = cvtpk(sp[6 * 33], sp[7 * 33]);
;         *(u32x4*)(WT + (size_t)(n0 + n) * K + k0 + 8 * c) = o; }
;     asm volatile("s_waitcnt lgkmcnt(0)" ::: "memory");
; }
; __global__ void __launch_bounds__(NWAVES * 64, 2) fwd(Args args) {
;     ...
;             const int first = split ? 224 : 0, nw = (G - first) * NWAVES;
;             if (bx >= first)
;                 for (int it = (bx - first) * NWAVES + wid; it < 2 * I_OUT; it += nw) {
;                     if (it < I_OUT) p0_transpose_item(w_out, DM, DM, WoutT, nullptr, scr, it, l3);
;                     else p0_transpose_item(w_gate, DM, DM, WgT, ple_norm, scr, it - I_OUT, l3);
;                 }
.LBB0_476:
	s_cmp_lt_u32 s77, 0xe0
	s_cbranch_scc1 .Ldw_skip
	s_load_dwordx2 s[50:51], s[80:81], 0x20018
	s_add_u32 s52, s80, 0x200000
	s_addc_u32 s53, s81, 0
	v_and_b32_e32 v16, 63, v185
	v_and_b32_e32 v2, 7, v16
	v_ashrrev_i32_e32 v9, 3, v16
	v_lshlrev_b32_e32 v6, 4, v2
	s_movk_i32 s48, 0x84
	v_add_u32_e32 v14, s61, v6
	v_mul_lo_u32 v15, v9, s48
	v_mov_b32_e32 v7, 0
	v_mul_u32_u24_e32 v4, 0x420, v2
	v_lshlrev_b32_e32 v5, 2, v9
	v_add_u32_e32 v14, v14, v15
	v_add3_u32 v13, s61, v4, v5
	s_waitcnt lgkmcnt(0)
	v_lshl_add_u64 v[4:5], s[50:51], 0, v[6:7]
	v_lshl_add_u64 v[6:7], s[52:53], 0, v[6:7]
	v_add_u32_e32 v15, 0x420, v14
	v_add_u32_e32 v17, 0x428, v14
	v_add_u32_e32 v18, 0x840, v14
	v_add_u32_e32 v19, 0x848, v14
	v_add_u32_e32 v20, 0xc60, v14
	v_add_u32_e32 v21, 0xc68, v14
	v_add_u32_e32 v22, 0x1080, v14
	v_add_u32_e32 v23, 0x1088, v14
	v_add_u32_e32 v24, 0x14a0, v14
	v_add_u32_e32 v25, 0x14a8, v14
	v_add_u32_e32 v26, 0x18c0, v14
	v_add_u32_e32 v27, 0x18c8, v14
	v_add_u32_e32 v28, 0x1ce0, v14
	v_add_u32_e32 v29, 0x1ce8, v14
	s_movk_i32 s42, 0x7000
	s_sub_i32 s43, s77, 0xe0
	s_lshl_b32 s43, s43, 3
	s_add_i32 s43, s43, s60
	s_mov_b32 s55, 0
.Ldw_loop:
	s_cmpk_gt_i32 s43, 0x139f
	s_cbranch_scc1 .Ldw_done
	s_cmpk_lt_u32 s43, 0x680
	s_cbranch_scc1 .Ldw_dec
	s_cmp_lg_u32 s55, 0
	s_cbranch_scc1 .Ldw_dec
	s_mov_b32 s55, 1
	s_waitcnt vmcnt(0)
	s_barrier
	s_cmp_lg_u32 s60, 0
	s_cbranch_scc1 .Ldw_dec
	v_mov_b32_e32 v0, 0
	v_mov_b32_e32 v1, 1
	s_mov_b64 s[46:47], exec
	s_mov_b64 exec, 1
	global_atomic_add v0, v1, s[88:89] offset:256
	s_mov_b64 exec, s[46:47]
.Ldw_dec:
	s_cmpk_lt_u32 s43, 0x5a0
	s_cbranch_scc0 .Ldw_c2
	s_mul_i32 s41, s43, 0x556
	s_lshr_b32 s41, s41, 16
	s_mul_i32 s44, s41, 48
	s_sub_i32 s44, s43, s44
	s_add_i32 s41, s41, 2
	s_cmp_ge_u32 s44, 24
	s_cselect_b32 s49, 0x78, 32
	s_add_i32 s44, s44, s49
	s_branch .Ldw_go
.Ldw_c2:
	s_cmpk_lt_u32 s43, 0x680
	s_cbranch_scc0 .Ldw_c3
	s_sub_i32 s44, s43, 0x5a0
	s_cmp_ge_u32 s44, 0x70
	s_cselect_b32 s41, 1, 0
	s_cselect_b32 s49, 0x70, 0
	s_sub_i32 s44, s44, s49
	s_branch .Ldw_n23
.Ldw_c3:
	s_sub_i32 s44, s43, 0x680
	s_mul_i32 s41, s44, 0x925
	s_lshr_b32 s41, s41, 18
	s_mul_i32 s49, s41, 0x70
	s_sub_i32 s44, s44, s49
	s_add_i32 s41, s41, 2
.Ldw_n23:
	s_cmp_ge_u32 s44, 56
	s_cselect_b32 s49, 0x70, 56
	s_add_i32 s44, s44, s49
.Ldw_go:
	s_lshl_b32 s44, s44, 5
	s_lshl_b32 s40, s41, 6
	s_ashr_i32 s45, s44, 31
	v_add_u32_e32 v60, s40, v9
	v_lshl_add_u64 v[58:59], s[44:45], 2, v[4:5]
	v_mad_i64_i32 v[38:39], s[46:47], v60, s42, v[58:59]
	v_add_u32_e32 v30, 8, v60
	v_mad_i64_i32 v[40:41], s[46:47], v30, s42, v[58:59]
	global_load_dwordx4 v[30:33], v[38:39], off nt
	global_load_dwordx4 v[34:37], v[40:41], off nt
	v_add_u32_e32 v38, 16, v60
	v_mad_i64_i32 v[46:47], s[46:47], v38, s42, v[58:59]
	v_add_u32_e32 v38, 24, v60
	v_mad_i64_i32 v[48:49], s[46:47], v38, s42, v[58:59]
	global_load_dwordx4 v[38:41], v[46:47], off nt
	global_load_dwordx4 v[42:45], v[48:49], off nt
	v_add_u32_e32 v46, 32, v60
	v_mad_i64_i32 v[54:55], s[46:47], v46, s42, v[58:59]
	v_add_u32_e32 v46, 40, v60
	v_mad_i64_i32 v[56:57], s[46:47], v46, s42, v[58:59]
	global_load_dwordx4 v[46:49], v[54:55], off nt
	global_load_dwordx4 v[50:53], v[56:57], off nt
	v_add_u32_e32 v54, 48, v60
	v_mad_i64_i32 v[54:55], s[46:47], v54, s42, v[58:59]
	global_load_dwordx4 v[54:57], v[54:55], off nt
	v_add_u32_e32 v60, 56, v60
	v_mad_i64_i32 v[58:59], s[46:47], v60, s42, v[58:59]
	global_load_dwordx4 v[58:61], v[58:59], off nt
	v_add_u32_e32 v64, s44, v9
	s_ashr_i32 s41, s40, 31
	v_ashrrev_i32_e32 v65, 31, v64
	v_add_u32_e32 v66, 8, v64
	v_lshl_add_u64 v[62:63], s[40:41], 1, v[6:7]
	v_lshlrev_b64 v[68:69], 12, v[64:65]
	v_ashrrev_i32_e32 v67, 31, v66
	v_lshl_add_u64 v[68:69], v[62:63], 0, v[68:69]
	v_lshlrev_b64 v[66:67], 12, v[66:67]
	v_lshl_add_u64 v[66:67], v[62:63], 0, v[66:67]
	s_waitcnt vmcnt(7)
	ds_write2_b32 v14, v30, v31 offset1:1
	ds_write2_b32 v14, v32, v33 offset0:2 offset1:3
	s_waitcnt vmcnt(6)
	ds_write2_b32 v15, v34, v35 offset1:1
	ds_write2_b32 v17, v36, v37 offset1:1
	s_waitcnt vmcnt(5)
	ds_write2_b32 v18, v38, v39 offset1:1
	ds_write2_b32 v19, v40, v41 offset1:1
	s_waitcnt vmcnt(4)
	ds_write2_b32 v20, v42, v43 offset1:1
	ds_write2_b32 v21, v44, v45 offset1:1
	s_waitcnt vmcnt(3)
	ds_write2_b32 v22, v46, v47 offset1:1
	ds_write2_b32 v23, v48, v49 offset1:1
	s_waitcnt vmcnt(2)
	ds_write2_b32 v24, v50, v51 offset1:1
	ds_write2_b32 v25, v52, v53 offset1:1
	s_waitcnt vmcnt(1)
	ds_write2_b32 v26, v54, v55 offset1:1
	ds_write2_b32 v27, v56, v57 offset1:1
	s_waitcnt vmcnt(0)
	ds_write2_b32 v28, v58, v59 offset1:1
	ds_write2_b32 v29, v60, v61 offset1:1
	s_waitcnt lgkmcnt(0)
	ds_read2_b32 v[32:33], v13 offset0:33 offset1:41
	ds_read2_b32 v[34:35], v13 offset1:8
	ds_read2_b32 v[36:37], v13 offset0:66 offset1:74
	ds_read2_b32 v[38:39], v13 offset0:99 offset1:107
	ds_read2_b32 v[40:41], v13 offset0:132 offset1:140
	ds_read2_b32 v[42:43], v13 offset0:165 offset1:173
	ds_read2_b32 v[44:45], v13 offset0:198 offset1:206
	ds_read2_b32 v[46:47], v13 offset0:231 offset1:239
	ds_read2_b32 v[48:49], v13 offset0:49 offset1:57
	ds_read2_b32 v[50:51], v13 offset0:16 offset1:24
	ds_read2_b32 v[52:53], v13 offset0:82 offset1:90
	ds_read2_b32 v[54:55], v13 offset0:115 offset1:123
	ds_read2_b32 v[56:57], v13 offset0:148 offset1:156
	ds_read2_b32 v[58:59], v13 offset0:181 offset1:189
	ds_read2_b32 v[60:61], v13 offset0:214 offset1:222
	ds_read2_b32 v[70:71], v13 offset0:247 offset1:255
	s_waitcnt lgkmcnt(14)
	v_cvt_pk_bf16_f32 v30, v34, v32
	s_waitcnt lgkmcnt(12)
	v_cvt_pk_bf16_f32 v31, v36, v38
	v_cvt_pk_bf16_f32 v34, v35, v33
	s_waitcnt lgkmcnt(10)
	v_cvt_pk_bf16_f32 v32, v40, v42
	s_waitcnt lgkmcnt(8)
	v_cvt_pk_bf16_f32 v33, v44, v46
	v_cvt_pk_bf16_f32 v35, v37, v39
	v_cvt_pk_bf16_f32 v36, v41, v43
	v_cvt_pk_bf16_f32 v37, v45, v47
	global_store_dwordx4 v[68:69], v[30:33], off sc1
	global_store_dwordx4 v[66:67], v[34:37], off sc1
	s_waitcnt lgkmcnt(6)
	v_cvt_pk_bf16_f32 v38, v50, v48
	v_add_u32_e32 v30, 16, v64
	v_ashrrev_i32_e32 v31, 31, v30
	v_add_u32_e32 v34, 24, v64
	v_lshlrev_b64 v[30:31], 12, v[30:31]
	v_ashrrev_i32_e32 v35, 31, v34
	s_waitcnt lgkmcnt(4)
	v_cvt_pk_bf16_f32 v39, v52, v54
	s_waitcnt lgkmcnt(2)
	v_cvt_pk_bf16_f32 v40, v56, v58
	s_waitcnt lgkmcnt(0)
	v_cvt_pk_bf16_f32 v41, v60, v70
	v_lshl_add_u64 v[30:31], v[62:63], 0, v[30:31]
	v_lshlrev_b64 v[34:35], 12, v[34:35]
	global_store_dwordx4 v[30:31], v[38:41], off sc1
	v_cvt_pk_bf16_f32 v30, v51, v49
	v_cvt_pk_bf16_f32 v31, v53, v55
	v_cvt_pk_bf16_f32 v32, v57, v59
	v_cvt_pk_bf16_f32 v33, v61, v71
	v_lshl_add_u64 v[34:35], v[62:63], 0, v[34:35]
	global_store_dwordx4 v[34:35], v[30:33], off sc1
	s_waitcnt lgkmcnt(0)
	s_add_i32 s43, s43, 0x100
	s_branch .Ldw_loop
.Ldw_done:
	s_waitcnt vmcnt(0)
	s_barrier
	s_cmp_lg_u32 s60, 0
	s_cbranch_scc1 .Ldw_skip
	v_mov_b32_e32 v0, 0
	v_mov_b32_e32 v1, 1
	s_mov_b64 s[46:47], exec
	s_mov_b64 exec, 1
	global_atomic_add v0, v1, s[88:89] offset:256
	s_mov_b64 exec, s[46:47]
